# grid barrier: the arrival atomic is issued before the L1 invalidate and its return is awaited with vmcnt(1), leaving the invalidate in flight
# baseline (speedup 1.0000x reference)
.LBB0_87:
	s_mov_b64 s[8:9], exec
	s_lshl_b32 s3, s67, 8
	v_mbcnt_lo_u32_b32 v3, s8, 0
	s_add_u32 s6, s68, s3
	v_mbcnt_hi_u32_b32 v3, s9, v3
	s_addc_u32 s7, s69, 0
	v_cmp_eq_u32_e32 vcc, 0, v3
	s_and_saveexec_b64 s[10:11], vcc
	s_cbranch_execz .LBB0_89
	s_bcnt1_i32_b64 s3, s[8:9]
	v_mov_b32_e32 v5, 0x1000
	v_mov_b32_e32 v6, s3
	global_atomic_add v5, v5, v6, s[6:7] offset:1024 sc0
	buffer_inv sc1
.LBB0_89:
	s_or_b64 exec, exec, s[10:11]
	v_cvt_f32_u32_e32 v6, v4
	s_waitcnt vmcnt(1)
	v_readfirstlane_b32 s3, v5
	v_sub_u32_e32 v5, 0, v4
	v_rcp_iflag_f32_e32 v6, v6
	v_add_u32_e32 v7, s3, v3
	v_mul_f32_e32 v6, 0x4f7ffffe, v6
	v_cvt_u32_f32_e32 v6, v6
	v_mul_lo_u32 v3, v5, v6
	v_mul_hi_u32 v3, v6, v3
	v_add_u32_e32 v3, v6, v3
	v_mul_hi_u32 v3, v7, v3
	v_mul_lo_u32 v5, v3, v4
	v_sub_u32_e32 v5, v7, v5
	v_add_u32_e32 v6, 1, v3
	v_cmp_ge_u32_e32 vcc, v5, v4
	s_nop 1
	v_cndmask_b32_e32 v3, v3, v6, vcc
	v_sub_u32_e32 v6, v5, v4
	v_cndmask_b32_e32 v5, v5, v6, vcc
	v_add_u32_e32 v6, 1, v3
	v_cmp_ge_u32_e32 vcc, v5, v4
	v_add_u32_e32 v5, 1, v7
	s_nop 0
	v_cndmask_b32_e32 v3, v3, v6, vcc
	v_mul_lo_u32 v6, v4, v3
	v_add_u32_e32 v4, v6, v4
	v_cmp_ne_u32_e32 vcc, v5, v4
	s_and_saveexec_b64 s[8:9], vcc
	s_xor_b64 s[8:9], exec, s[8:9]
	s_cbranch_execz .LBB0_103
	s_waitcnt lgkmcnt(0)
	v_mov_b32_e32 v2, 0x2000
	global_load_dword v2, v2, s[6:7] offset:1024 sc1
	s_add_u32 s14, s6, 0x2400
	s_addc_u32 s15, s7, 0
	s_waitcnt vmcnt(0)
	v_cmp_eq_u32_e32 vcc, v2, v3
	s_and_saveexec_b64 s[10:11], vcc
	s_cbranch_execz .LBB0_102
	s_add_u32 s12, s96, 0xd3a0200
	s_addc_u32 s13, s97, 0
	s_mov_b32 s3, 1
	s_mov_b64 s[16:17], 0
	v_mov_b32_e32 v2, 0
	s_branch .LBB0_93

.LBB0_415:
	s_mov_b64 s[6:7], exec
	s_lshl_b32 s3, s67, 8
	v_mbcnt_lo_u32_b32 v3, s6, 0
	s_add_u32 s4, s68, s3
	v_mbcnt_hi_u32_b32 v3, s7, v3
	s_addc_u32 s5, s69, 0
	v_cmp_eq_u32_e32 vcc, 0, v3
	s_and_saveexec_b64 s[8:9], vcc
	s_cbranch_execz .LBB0_417
	s_bcnt1_i32_b64 s3, s[6:7]
	v_mov_b32_e32 v5, 0x1000
	v_mov_b32_e32 v6, s3
	global_atomic_add v5, v5, v6, s[4:5] offset:1024 sc0
	buffer_inv sc1
.LBB0_417:
	s_or_b64 exec, exec, s[8:9]
	v_cvt_f32_u32_e32 v6, v4
	s_waitcnt vmcnt(1)
	v_readfirstlane_b32 s3, v5
	v_sub_u32_e32 v5, 0, v4
	v_rcp_iflag_f32_e32 v6, v6
	v_add_u32_e32 v7, s3, v3
	v_mul_f32_e32 v6, 0x4f7ffffe, v6
	v_cvt_u32_f32_e32 v6, v6
	v_mul_lo_u32 v3, v5, v6
	v_mul_hi_u32 v3, v6, v3
	v_add_u32_e32 v3, v6, v3
	v_mul_hi_u32 v3, v7, v3
	v_mul_lo_u32 v5, v3, v4
	v_sub_u32_e32 v5, v7, v5
	v_add_u32_e32 v6, 1, v3
	v_cmp_ge_u32_e32 vcc, v5, v4
	s_nop 1
	v_cndmask_b32_e32 v3, v3, v6, vcc
	v_sub_u32_e32 v6, v5, v4
	v_cndmask_b32_e32 v5, v5, v6, vcc
	v_add_u32_e32 v6, 1, v3
	v_cmp_ge_u32_e32 vcc, v5, v4
	v_add_u32_e32 v5, 1, v7
	s_nop 0
	v_cndmask_b32_e32 v3, v3, v6, vcc
	v_mul_lo_u32 v6, v4, v3
	v_add_u32_e32 v4, v6, v4
	v_cmp_ne_u32_e32 vcc, v5, v4
	s_and_saveexec_b64 s[6:7], vcc
	s_xor_b64 s[6:7], exec, s[6:7]
	s_cbranch_execz .LBB0_431
	s_waitcnt lgkmcnt(0)
	v_mov_b32_e32 v2, 0x2000
	global_load_dword v2, v2, s[4:5] offset:1024 sc1
	s_add_u32 s12, s4, 0x2400
	s_addc_u32 s13, s5, 0
	s_waitcnt vmcnt(0)
	v_cmp_eq_u32_e32 vcc, v2, v3
	s_and_saveexec_b64 s[8:9], vcc
	s_cbranch_execz .LBB0_430
	s_add_u32 s10, s96, 0xd3a0200
	s_addc_u32 s11, s97, 0
	s_mov_b32 s3, 1
	s_mov_b64 s[14:15], 0
	v_mov_b32_e32 v2, 0
	s_branch .LBB0_421

.LBB0_586:
	s_mov_b64 s[8:9], exec
	s_lshl_b32 s3, s67, 8
	v_mbcnt_lo_u32_b32 v2, s8, 0
	s_add_u32 s6, s68, s3
	v_mbcnt_hi_u32_b32 v2, s9, v2
	s_addc_u32 s7, s69, 0
	v_cmp_eq_u32_e32 vcc, 0, v2
	s_and_saveexec_b64 s[10:11], vcc
	s_cbranch_execz .LBB0_588
	s_bcnt1_i32_b64 s3, s[8:9]
	v_mov_b32_e32 v4, 0x1000
	v_mov_b32_e32 v5, s3
	global_atomic_add v4, v4, v5, s[6:7] offset:1024 sc0
	buffer_inv sc1
.LBB0_588:
	s_or_b64 exec, exec, s[10:11]
	v_cvt_f32_u32_e32 v5, v3
	s_waitcnt vmcnt(1)
	v_readfirstlane_b32 s3, v4
	v_sub_u32_e32 v4, 0, v3
	v_rcp_iflag_f32_e32 v5, v5
	v_add_u32_e32 v6, s3, v2
	v_mul_f32_e32 v5, 0x4f7ffffe, v5
	v_cvt_u32_f32_e32 v5, v5
	v_mul_lo_u32 v2, v4, v5
	v_mul_hi_u32 v2, v5, v2
	v_add_u32_e32 v2, v5, v2
	v_mul_hi_u32 v2, v6, v2
	v_mul_lo_u32 v4, v2, v3
	v_sub_u32_e32 v4, v6, v4
	v_add_u32_e32 v5, 1, v2
	v_cmp_ge_u32_e32 vcc, v4, v3
	s_nop 1
	v_cndmask_b32_e32 v2, v2, v5, vcc
	v_sub_u32_e32 v5, v4, v3
	v_cndmask_b32_e32 v4, v4, v5, vcc
	v_add_u32_e32 v5, 1, v2
	v_cmp_ge_u32_e32 vcc, v4, v3
	v_add_u32_e32 v4, 1, v6
	s_nop 0
	v_cndmask_b32_e32 v2, v2, v5, vcc
	v_mul_lo_u32 v5, v3, v2
	v_add_u32_e32 v3, v5, v3
	v_cmp_ne_u32_e32 vcc, v4, v3
	s_and_saveexec_b64 s[8:9], vcc
	s_xor_b64 s[8:9], exec, s[8:9]
	s_cbranch_execz .LBB0_602
	s_waitcnt lgkmcnt(0)
	v_mov_b32_e32 v1, 0x2000
	global_load_dword v1, v1, s[6:7] offset:1024 sc1
	s_add_u32 s14, s6, 0x2400
	s_addc_u32 s15, s7, 0
	s_waitcnt vmcnt(0)
	v_cmp_eq_u32_e32 vcc, v1, v2
	s_and_saveexec_b64 s[10:11], vcc
	s_cbranch_execz .LBB0_601
	s_add_u32 s12, s96, 0xd3a0200
	s_addc_u32 s13, s97, 0
	s_mov_b32 s3, 1
	s_mov_b64 s[16:17], 0
	v_mov_b32_e32 v1, 0
	s_branch .LBB0_592

.LBB0_661:
	s_mov_b64 s[10:11], exec
	s_lshl_b32 s3, s67, 8
	v_mbcnt_lo_u32_b32 v2, s10, 0
	s_add_u32 s8, s68, s3
	v_mbcnt_hi_u32_b32 v2, s11, v2
	s_addc_u32 s9, s69, 0
	v_cmp_eq_u32_e32 vcc, 0, v2
	s_and_saveexec_b64 s[12:13], vcc
	s_cbranch_execz .LBB0_663
	s_bcnt1_i32_b64 s3, s[10:11]
	v_mov_b32_e32 v4, 0x1000
	v_mov_b32_e32 v5, s3
	global_atomic_add v4, v4, v5, s[8:9] offset:1024 sc0
	buffer_inv sc1
.LBB0_663:
	s_or_b64 exec, exec, s[12:13]
	v_cvt_f32_u32_e32 v5, v3
	s_waitcnt vmcnt(1)
	v_readfirstlane_b32 s3, v4
	v_sub_u32_e32 v4, 0, v3
	v_rcp_iflag_f32_e32 v5, v5
	v_add_u32_e32 v6, s3, v2
	v_mul_f32_e32 v5, 0x4f7ffffe, v5
	v_cvt_u32_f32_e32 v5, v5
	v_mul_lo_u32 v2, v4, v5
	v_mul_hi_u32 v2, v5, v2
	v_add_u32_e32 v2, v5, v2
	v_mul_hi_u32 v2, v6, v2
	v_mul_lo_u32 v4, v2, v3
	v_sub_u32_e32 v4, v6, v4
	v_add_u32_e32 v5, 1, v2
	v_cmp_ge_u32_e32 vcc, v4, v3
	s_nop 1
	v_cndmask_b32_e32 v2, v2, v5, vcc
	v_sub_u32_e32 v5, v4, v3
	v_cndmask_b32_e32 v4, v4, v5, vcc
	v_add_u32_e32 v5, 1, v2
	v_cmp_ge_u32_e32 vcc, v4, v3
	v_add_u32_e32 v4, 1, v6
	s_nop 0
	v_cndmask_b32_e32 v2, v2, v5, vcc
	v_mul_lo_u32 v5, v3, v2
	v_add_u32_e32 v3, v5, v3
	v_cmp_ne_u32_e32 vcc, v4, v3
	s_and_saveexec_b64 s[10:11], vcc
	s_xor_b64 s[10:11], exec, s[10:11]
	s_cbranch_execz .LBB0_677
	s_waitcnt lgkmcnt(0)
	v_mov_b32_e32 v1, 0x2000
	global_load_dword v1, v1, s[8:9] offset:1024 sc1
	s_add_u32 s16, s8, 0x2400
	s_addc_u32 s17, s9, 0
	s_waitcnt vmcnt(0)
	v_cmp_eq_u32_e32 vcc, v1, v2
	s_and_saveexec_b64 s[12:13], vcc
	s_cbranch_execz .LBB0_676
	s_add_u32 s14, s96, 0xd3a0200
	s_addc_u32 s15, s97, 0
	s_mov_b32 s3, 1
	s_mov_b64 s[18:19], 0
	v_mov_b32_e32 v1, 0
	s_branch .LBB0_667

.LBB0_840:
	s_mov_b64 s[10:11], exec
	s_lshl_b32 s3, s67, 8
	v_mbcnt_lo_u32_b32 v1, s10, 0
	s_add_u32 s8, s68, s3
	v_mbcnt_hi_u32_b32 v1, s11, v1
	s_addc_u32 s9, s69, 0
	v_cmp_eq_u32_e32 vcc, 0, v1
	s_and_saveexec_b64 s[12:13], vcc
	s_cbranch_execz .LBB0_842
	s_bcnt1_i32_b64 s3, s[10:11]
	v_mov_b32_e32 v3, 0x1000
	v_mov_b32_e32 v4, s3
	global_atomic_add v3, v3, v4, s[8:9] offset:1024 sc0
	buffer_inv sc1
.LBB0_842:
	s_or_b64 exec, exec, s[12:13]
	v_cvt_f32_u32_e32 v4, v2
	s_waitcnt vmcnt(1)
	v_readfirstlane_b32 s3, v3
	v_sub_u32_e32 v3, 0, v2
	v_rcp_iflag_f32_e32 v4, v4
	v_add_u32_e32 v5, s3, v1
	v_mul_f32_e32 v4, 0x4f7ffffe, v4
	v_cvt_u32_f32_e32 v4, v4
	v_mul_lo_u32 v1, v3, v4
	v_mul_hi_u32 v1, v4, v1
	v_add_u32_e32 v1, v4, v1
	v_mul_hi_u32 v1, v5, v1
	v_mul_lo_u32 v3, v1, v2
	v_sub_u32_e32 v3, v5, v3
	v_add_u32_e32 v4, 1, v1
	v_cmp_ge_u32_e32 vcc, v3, v2
	s_nop 1
	v_cndmask_b32_e32 v1, v1, v4, vcc
	v_sub_u32_e32 v4, v3, v2
	v_cndmask_b32_e32 v3, v3, v4, vcc
	v_add_u32_e32 v4, 1, v1
	v_cmp_ge_u32_e32 vcc, v3, v2
	v_add_u32_e32 v3, 1, v5
	s_nop 0
	v_cndmask_b32_e32 v1, v1, v4, vcc
	v_mul_lo_u32 v4, v2, v1
	v_add_u32_e32 v2, v4, v2
	v_cmp_ne_u32_e32 vcc, v3, v2
	s_and_saveexec_b64 s[10:11], vcc
	s_xor_b64 s[10:11], exec, s[10:11]
	s_cbranch_execz .LBB0_856
	s_waitcnt lgkmcnt(0)
	v_mov_b32_e32 v0, 0x2000
	global_load_dword v0, v0, s[8:9] offset:1024 sc1
	s_add_u32 s16, s8, 0x2400
	s_addc_u32 s17, s9, 0
	s_waitcnt vmcnt(0)
	v_cmp_eq_u32_e32 vcc, v0, v1
	s_and_saveexec_b64 s[12:13], vcc
	s_cbranch_execz .LBB0_855
	s_add_u32 s14, s96, 0xd3a0200
	s_addc_u32 s15, s97, 0
	s_mov_b32 s3, 1
	s_mov_b64 s[18:19], 0
	v_mov_b32_e32 v0, 0
	s_branch .LBB0_846
